# EpiRes hand-pipelined epilogue using packed f32 ops (v_pk_fma/v_pk_add) instead of scalar pairs
# speedup vs baseline: 1.0053x; 1.0031x over previous
;     __device__ __forceinline__ void operator()(const f32x4 (&acc)[2][2][4][2], const Unit& u, int wr_in, int wc_in, int fr_in, int fq_in) const {
;     ...
;             for (int bj = 0; bj < 2; ++bj) {
;                 const int col0 = colw + bj * 128;
;                 f32x4 x[4][2];
; #pragma unroll
;                 for (int m = 0; m < 4; ++m) { const float* p = src + (size_t)(rbase + ai * 128 + m) * DM + col0; x[m][0] = *(const f32x4*)(p); x[m][1] = *(const f32x4*)(p + 4); }
;                 const f32x4 g0 = *(const f32x4*)(gp + col0), g1 = *(const f32x4*)(gp + col0 + 4);
;                 f32x4 b0 = (f32x4){0.f, 0.f, 0.f, 0.f}, b1 = b0;
;                 if (bias) { b0 = *(const f32x4*)(bias + col0); b1 = *(const f32x4*)(bias + col0 + 4); }
; #pragma unroll
;                 for (int m = 0; m < 4; ++m) {
;                     float* q = dst + (size_t)(rbase + ai * 128 + m) * DM + col0;
;                     const f32x4 r0 = x[m][0] * sa[m] + sb[m] + g0 * (acc[ai][bj][m][0] + b0), r1 = x[m][1] * sa[m] + sb[m] + g1 * (acc[ai][bj][m][1] + b1);
;                     *(f32x4*)(q) = r0; *(f32x4*)(q + 4) = r1;
;                 }
.Lres_noconv:
	v_pk_fma_f32 v[146:147], v[146:147], v[204:205], v[204:205] op_sel:[0,1,0] op_sel_hi:[1,1,0]
	v_pk_fma_f32 v[148:149], v[148:149], v[204:205], v[204:205] op_sel:[0,1,0] op_sel_hi:[1,1,0]
	v_pk_fma_f32 v[150:151], v[150:151], v[204:205], v[204:205] op_sel:[0,1,0] op_sel_hi:[1,1,0]
	v_pk_fma_f32 v[152:153], v[152:153], v[204:205], v[204:205] op_sel:[0,1,0] op_sel_hi:[1,1,0]
	v_pk_fma_f32 v[154:155], v[154:155], v[206:207], v[206:207] op_sel:[0,1,0] op_sel_hi:[1,1,0]
	v_pk_fma_f32 v[156:157], v[156:157], v[206:207], v[206:207] op_sel:[0,1,0] op_sel_hi:[1,1,0]
	v_pk_fma_f32 v[158:159], v[158:159], v[206:207], v[206:207] op_sel:[0,1,0] op_sel_hi:[1,1,0]
	v_pk_fma_f32 v[160:161], v[160:161], v[206:207], v[206:207] op_sel:[0,1,0] op_sel_hi:[1,1,0]
	v_pk_fma_f32 v[162:163], v[162:163], v[208:209], v[208:209] op_sel:[0,1,0] op_sel_hi:[1,1,0]
	v_pk_fma_f32 v[164:165], v[164:165], v[208:209], v[208:209] op_sel:[0,1,0] op_sel_hi:[1,1,0]
	v_pk_fma_f32 v[166:167], v[166:167], v[208:209], v[208:209] op_sel:[0,1,0] op_sel_hi:[1,1,0]
	v_pk_fma_f32 v[168:169], v[168:169], v[208:209], v[208:209] op_sel:[0,1,0] op_sel_hi:[1,1,0]
	v_pk_fma_f32 v[170:171], v[170:171], v[210:211], v[210:211] op_sel:[0,1,0] op_sel_hi:[1,1,0]
	v_pk_fma_f32 v[172:173], v[172:173], v[210:211], v[210:211] op_sel:[0,1,0] op_sel_hi:[1,1,0]
	v_pk_fma_f32 v[174:175], v[174:175], v[210:211], v[210:211] op_sel:[0,1,0] op_sel_hi:[1,1,0]
	v_pk_fma_f32 v[176:177], v[176:177], v[210:211], v[210:211] op_sel:[0,1,0] op_sel_hi:[1,1,0]
	v_pk_add_f32 v[126:127], v[126:127], v[130:131]
	v_pk_add_f32 v[128:129], v[128:129], v[132:133]
	v_pk_add_f32 v[122:123], v[122:123], v[134:135]
	v_pk_add_f32 v[124:125], v[124:125], v[136:137]
	v_pk_add_f32 v[118:119], v[118:119], v[130:131]
	v_pk_add_f32 v[120:121], v[120:121], v[132:133]
	v_pk_add_f32 v[114:115], v[114:115], v[134:135]
	v_pk_add_f32 v[116:117], v[116:117], v[136:137]
	v_pk_add_f32 v[110:111], v[110:111], v[130:131]
	v_pk_add_f32 v[112:113], v[112:113], v[132:133]
	v_pk_add_f32 v[106:107], v[106:107], v[134:135]
	v_pk_add_f32 v[108:109], v[108:109], v[136:137]
	v_pk_add_f32 v[102:103], v[102:103], v[130:131]
	v_pk_add_f32 v[104:105], v[104:105], v[132:133]
	v_pk_add_f32 v[98:99], v[98:99], v[134:135]
	v_pk_add_f32 v[100:101], v[100:101], v[136:137]
	v_pk_fma_f32 v[126:127], v[220:221], v[126:127], v[146:147]
	v_pk_fma_f32 v[128:129], v[222:223], v[128:129], v[148:149]
	v_pk_fma_f32 v[122:123], v[224:225], v[122:123], v[150:151]
	v_pk_fma_f32 v[124:125], v[226:227], v[124:125], v[152:153]
	v_pk_fma_f32 v[118:119], v[220:221], v[118:119], v[154:155]
	v_pk_fma_f32 v[120:121], v[222:223], v[120:121], v[156:157]
	v_pk_fma_f32 v[114:115], v[224:225], v[114:115], v[158:159]
	v_pk_fma_f32 v[116:117], v[226:227], v[116:117], v[160:161]
	v_pk_fma_f32 v[110:111], v[220:221], v[110:111], v[162:163]
	v_pk_fma_f32 v[112:113], v[222:223], v[112:113], v[164:165]
	v_pk_fma_f32 v[106:107], v[224:225], v[106:107], v[166:167]
	v_pk_fma_f32 v[108:109], v[226:227], v[108:109], v[168:169]
	v_pk_fma_f32 v[102:103], v[220:221], v[102:103], v[170:171]
	v_pk_fma_f32 v[104:105], v[222:223], v[104:105], v[172:173]
	v_pk_fma_f32 v[98:99], v[224:225], v[98:99], v[174:175]
	v_pk_fma_f32 v[100:101], v[226:227], v[100:101], v[176:177]
	global_store_dwordx4 v192, v[126:129], s[48:49]
	global_store_dwordx4 v192, v[122:125], s[48:49] offset:16
	global_store_dwordx4 v193, v[118:121], s[48:49]
	global_store_dwordx4 v193, v[114:117], s[48:49] offset:16
	global_store_dwordx4 v194, v[110:113], s[48:49]
	global_store_dwordx4 v194, v[106:109], s[48:49] offset:16
	global_store_dwordx4 v195, v[102:105], s[48:49]
	global_store_dwordx4 v195, v[98:101], s[48:49] offset:16
	global_load_dwordx4 v[146:149], v192, s[0:1] offset:512
	global_load_dwordx4 v[150:153], v192, s[0:1] offset:528
	global_load_dwordx4 v[154:157], v193, s[0:1] offset:512
	global_load_dwordx4 v[158:161], v193, s[0:1] offset:528
	global_load_dwordx4 v[162:165], v194, s[0:1] offset:512
	global_load_dwordx4 v[166:169], v194, s[0:1] offset:528
	global_load_dwordx4 v[170:173], v195, s[0:1] offset:512
	global_load_dwordx4 v[174:177], v195, s[0:1] offset:528
	global_load_dwordx4 v[98:101], v196, s[0:1]
	global_load_dwordx4 v[102:105], v196, s[0:1] offset:16
	global_load_dwordx4 v[106:109], v197, s[0:1]
	global_load_dwordx4 v[110:113], v197, s[0:1] offset:16
	global_load_dwordx4 v[114:117], v198, s[0:1]
	global_load_dwordx4 v[118:121], v198, s[0:1] offset:16
	global_load_dwordx4 v[122:125], v199, s[0:1]
	global_load_dwordx4 v[126:129], v199, s[0:1] offset:16
	s_waitcnt vmcnt(8)
;     __device__ __forceinline__ void operator()(const f32x4 (&acc)[2][2][4][2], const Unit& u, int wr_in, int wc_in, int fr_in, int fq_in) const {
;     ...
;             for (int bj = 0; bj < 2; ++bj) {
;                 const int col0 = colw + bj * 128;
;                 f32x4 x[4][2];
; #pragma unroll
;                 for (int m = 0; m < 4; ++m) { const float* p = src + (size_t)(rbase + ai * 128 + m) * DM + col0; x[m][0] = *(const f32x4*)(p); x[m][1] = *(const f32x4*)(p + 4); }
;                 const f32x4 g0 = *(const f32x4*)(gp + col0), g1 = *(const f32x4*)(gp + col0 + 4);
;                 f32x4 b0 = (f32x4){0.f, 0.f, 0.f, 0.f}, b1 = b0;
;                 if (bias) { b0 = *(const f32x4*)(bias + col0); b1 = *(const f32x4*)(bias + col0 + 4); }
; #pragma unroll
;                 for (int m = 0; m < 4; ++m) {
;                     float* q = dst + (size_t)(rbase + ai * 128 + m) * DM + col0;
;                     const f32x4 r0 = x[m][0] * sa[m] + sb[m] + g0 * (acc[ai][bj][m][0] + b0), r1 = x[m][1] * sa[m] + sb[m] + g1 * (acc[ai][bj][m][1] + b1);
;                     *(f32x4*)(q) = r0; *(f32x4*)(q + 4) = r1;
;                 }
	v_pk_fma_f32 v[146:147], v[146:147], v[204:205], v[204:205] op_sel:[0,1,0] op_sel_hi:[1,1,0]
	v_pk_fma_f32 v[148:149], v[148:149], v[204:205], v[204:205] op_sel:[0,1,0] op_sel_hi:[1,1,0]
	v_pk_fma_f32 v[150:151], v[150:151], v[204:205], v[204:205] op_sel:[0,1,0] op_sel_hi:[1,1,0]
	v_pk_fma_f32 v[152:153], v[152:153], v[204:205], v[204:205] op_sel:[0,1,0] op_sel_hi:[1,1,0]
	v_pk_fma_f32 v[154:155], v[154:155], v[206:207], v[206:207] op_sel:[0,1,0] op_sel_hi:[1,1,0]
	v_pk_fma_f32 v[156:157], v[156:157], v[206:207], v[206:207] op_sel:[0,1,0] op_sel_hi:[1,1,0]
	v_pk_fma_f32 v[158:159], v[158:159], v[206:207], v[206:207] op_sel:[0,1,0] op_sel_hi:[1,1,0]
	v_pk_fma_f32 v[160:161], v[160:161], v[206:207], v[206:207] op_sel:[0,1,0] op_sel_hi:[1,1,0]
	v_pk_fma_f32 v[162:163], v[162:163], v[208:209], v[208:209] op_sel:[0,1,0] op_sel_hi:[1,1,0]
	v_pk_fma_f32 v[164:165], v[164:165], v[208:209], v[208:209] op_sel:[0,1,0] op_sel_hi:[1,1,0]
	v_pk_fma_f32 v[166:167], v[166:167], v[208:209], v[208:209] op_sel:[0,1,0] op_sel_hi:[1,1,0]
	v_pk_fma_f32 v[168:169], v[168:169], v[208:209], v[208:209] op_sel:[0,1,0] op_sel_hi:[1,1,0]
	v_pk_fma_f32 v[170:171], v[170:171], v[210:211], v[210:211] op_sel:[0,1,0] op_sel_hi:[1,1,0]
	v_pk_fma_f32 v[172:173], v[172:173], v[210:211], v[210:211] op_sel:[0,1,0] op_sel_hi:[1,1,0]
	v_pk_fma_f32 v[174:175], v[174:175], v[210:211], v[210:211] op_sel:[0,1,0] op_sel_hi:[1,1,0]
	v_pk_fma_f32 v[176:177], v[176:177], v[210:211], v[210:211] op_sel:[0,1,0] op_sel_hi:[1,1,0]
	v_pk_add_f32 v[94:95], v[94:95], v[138:139]
	v_pk_add_f32 v[96:97], v[96:97], v[140:141]
	v_pk_add_f32 v[90:91], v[90:91], v[142:143]
	v_pk_add_f32 v[92:93], v[92:93], v[144:145]
	v_pk_add_f32 v[86:87], v[86:87], v[138:139]
	v_pk_add_f32 v[88:89], v[88:89], v[140:141]
	v_pk_add_f32 v[82:83], v[82:83], v[142:143]
	v_pk_add_f32 v[84:85], v[84:85], v[144:145]
	v_pk_add_f32 v[78:79], v[78:79], v[138:139]
	v_pk_add_f32 v[80:81], v[80:81], v[140:141]
	v_pk_add_f32 v[74:75], v[74:75], v[142:143]
	v_pk_add_f32 v[76:77], v[76:77], v[144:145]
	v_pk_add_f32 v[70:71], v[70:71], v[138:139]
	v_pk_add_f32 v[72:73], v[72:73], v[140:141]
	v_pk_add_f32 v[66:67], v[66:67], v[142:143]
	v_pk_add_f32 v[68:69], v[68:69], v[144:145]
	v_pk_fma_f32 v[94:95], v[228:229], v[94:95], v[146:147]
	v_pk_fma_f32 v[96:97], v[230:231], v[96:97], v[148:149]
	v_pk_fma_f32 v[90:91], v[232:233], v[90:91], v[150:151]
	v_pk_fma_f32 v[92:93], v[234:235], v[92:93], v[152:153]
	v_pk_fma_f32 v[86:87], v[228:229], v[86:87], v[154:155]
	v_pk_fma_f32 v[88:89], v[230:231], v[88:89], v[156:157]
	v_pk_fma_f32 v[82:83], v[232:233], v[82:83], v[158:159]
	v_pk_fma_f32 v[84:85], v[234:235], v[84:85], v[160:161]
	v_pk_fma_f32 v[78:79], v[228:229], v[78:79], v[162:163]
	v_pk_fma_f32 v[80:81], v[230:231], v[80:81], v[164:165]
	v_pk_fma_f32 v[74:75], v[232:233], v[74:75], v[166:167]
	v_pk_fma_f32 v[76:77], v[234:235], v[76:77], v[168:169]
	v_pk_fma_f32 v[70:71], v[228:229], v[70:71], v[170:171]
	v_pk_fma_f32 v[72:73], v[230:231], v[72:73], v[172:173]
	v_pk_fma_f32 v[66:67], v[232:233], v[66:67], v[174:175]
	v_pk_fma_f32 v[68:69], v[234:235], v[68:69], v[176:177]
	global_store_dwordx4 v192, v[94:97], s[48:49] offset:512
	global_store_dwordx4 v192, v[90:93], s[48:49] offset:528
	global_store_dwordx4 v193, v[86:89], s[48:49] offset:512
	global_store_dwordx4 v193, v[82:85], s[48:49] offset:528
	global_store_dwordx4 v194, v[78:81], s[48:49] offset:512
	global_store_dwordx4 v194, v[74:77], s[48:49] offset:528
	global_store_dwordx4 v195, v[70:73], s[48:49] offset:512
	global_store_dwordx4 v195, v[66:69], s[48:49] offset:528
	global_load_dwordx4 v[146:149], v196, s[0:1] offset:512
	global_load_dwordx4 v[150:153], v196, s[0:1] offset:528
	global_load_dwordx4 v[154:157], v197, s[0:1] offset:512
	global_load_dwordx4 v[158:161], v197, s[0:1] offset:528
	global_load_dwordx4 v[162:165], v198, s[0:1] offset:512
	global_load_dwordx4 v[166:169], v198, s[0:1] offset:528
	global_load_dwordx4 v[170:173], v199, s[0:1] offset:512
	global_load_dwordx4 v[174:177], v199, s[0:1] offset:528
	s_waitcnt vmcnt(16)
	v_pk_fma_f32 v[98:99], v[98:99], v[212:213], v[212:213] op_sel:[0,1,0] op_sel_hi:[1,1,0]
	v_pk_fma_f32 v[100:101], v[100:101], v[212:213], v[212:213] op_sel:[0,1,0] op_sel_hi:[1,1,0]
	v_pk_fma_f32 v[102:103], v[102:103], v[212:213], v[212:213] op_sel:[0,1,0] op_sel_hi:[1,1,0]
	v_pk_fma_f32 v[104:105], v[104:105], v[212:213], v[212:213] op_sel:[0,1,0] op_sel_hi:[1,1,0]
	v_pk_fma_f32 v[106:107], v[106:107], v[214:215], v[214:215] op_sel:[0,1,0] op_sel_hi:[1,1,0]
	v_pk_fma_f32 v[108:109], v[108:109], v[214:215], v[214:215] op_sel:[0,1,0] op_sel_hi:[1,1,0]
	v_pk_fma_f32 v[110:111], v[110:111], v[214:215], v[214:215] op_sel:[0,1,0] op_sel_hi:[1,1,0]
	v_pk_fma_f32 v[112:113], v[112:113], v[214:215], v[214:215] op_sel:[0,1,0] op_sel_hi:[1,1,0]
	v_pk_fma_f32 v[114:115], v[114:115], v[216:217], v[216:217] op_sel:[0,1,0] op_sel_hi:[1,1,0]
	v_pk_fma_f32 v[116:117], v[116:117], v[216:217], v[216:217] op_sel:[0,1,0] op_sel_hi:[1,1,0]
	v_pk_fma_f32 v[118:119], v[118:119], v[216:217], v[216:217] op_sel:[0,1,0] op_sel_hi:[1,1,0]
	v_pk_fma_f32 v[120:121], v[120:121], v[216:217], v[216:217] op_sel:[0,1,0] op_sel_hi:[1,1,0]
	v_pk_fma_f32 v[122:123], v[122:123], v[218:219], v[218:219] op_sel:[0,1,0] op_sel_hi:[1,1,0]
	v_pk_fma_f32 v[124:125], v[124:125], v[218:219], v[218:219] op_sel:[0,1,0] op_sel_hi:[1,1,0]
	v_pk_fma_f32 v[126:127], v[126:127], v[218:219], v[218:219] op_sel:[0,1,0] op_sel_hi:[1,1,0]
	v_pk_fma_f32 v[128:129], v[128:129], v[218:219], v[218:219] op_sel:[0,1,0] op_sel_hi:[1,1,0]
	v_pk_add_f32 v[62:63], v[62:63], v[130:131]
; #define PG8_BAR __builtin_amdgcn_s_barrier()
; template <class Epi>
; __device__ __forceinline__ void gemm_phase(LAS unsigned char* lds, const Gemm g, const StaticOrder& S, const Epi& E) {
;     ...
;         cur = nxt; cA = nA; cB = nB; ++ui;
;         if (wr == 1) PG8_BAR;
;     __device__ __forceinline__ void operator()(const f32x4 (&acc)[2][2][4][2], const Unit& u, int wr_in, int wc_in, int fr_in, int fq_in) const {
;     ...
;             for (int bj = 0; bj < 2; ++bj) {
;                 const int col0 = colw + bj * 128;
;                 f32x4 x[4][2];
; #pragma unroll
;                 for (int m = 0; m < 4; ++m) { const float* p = src + (size_t)(rbase + ai * 128 + m) * DM + col0; x[m][0] = *(const f32x4*)(p); x[m][1] = *(const f32x4*)(p + 4); }
;                 const f32x4 g0 = *(const f32x4*)(gp + col0), g1 = *(const f32x4*)(gp + col0 + 4);
;                 f32x4 b0 = (f32x4){0.f, 0.f, 0.f, 0.f}, b1 = b0;
;                 if (bias) { b0 = *(const f32x4*)(bias + col0); b1 = *(const f32x4*)(bias + col0 + 4); }
; #pragma unroll
;                 for (int m = 0; m < 4; ++m) {
;                     float* q = dst + (size_t)(rbase + ai * 128 + m) * DM + col0;
;                     const f32x4 r0 = x[m][0] * sa[m] + sb[m] + g0 * (acc[ai][bj][m][0] + b0), r1 = x[m][1] * sa[m] + sb[m] + g1 * (acc[ai][bj][m][1] + b1);
;                     *(f32x4*)(q) = r0; *(f32x4*)(q + 4) = r1;
;                 }
	v_pk_add_f32 v[64:65], v[64:65], v[132:133]
	v_pk_add_f32 v[58:59], v[58:59], v[134:135]
	v_pk_add_f32 v[60:61], v[60:61], v[136:137]
	v_pk_add_f32 v[54:55], v[54:55], v[130:131]
	v_pk_add_f32 v[56:57], v[56:57], v[132:133]
	v_pk_add_f32 v[50:51], v[50:51], v[134:135]
	v_pk_add_f32 v[52:53], v[52:53], v[136:137]
	v_pk_add_f32 v[46:47], v[46:47], v[130:131]
	v_pk_add_f32 v[48:49], v[48:49], v[132:133]
	v_pk_add_f32 v[42:43], v[42:43], v[134:135]
	v_pk_add_f32 v[44:45], v[44:45], v[136:137]
	v_pk_add_f32 v[38:39], v[38:39], v[130:131]
	v_pk_add_f32 v[40:41], v[40:41], v[132:133]
	v_pk_add_f32 v[34:35], v[34:35], v[134:135]
	v_pk_add_f32 v[36:37], v[36:37], v[136:137]
	v_pk_fma_f32 v[62:63], v[220:221], v[62:63], v[98:99]
	v_pk_fma_f32 v[64:65], v[222:223], v[64:65], v[100:101]
	v_pk_fma_f32 v[58:59], v[224:225], v[58:59], v[102:103]
	v_pk_fma_f32 v[60:61], v[226:227], v[60:61], v[104:105]
	v_pk_fma_f32 v[54:55], v[220:221], v[54:55], v[106:107]
	v_pk_fma_f32 v[56:57], v[222:223], v[56:57], v[108:109]
	v_pk_fma_f32 v[50:51], v[224:225], v[50:51], v[110:111]
	v_pk_fma_f32 v[52:53], v[226:227], v[52:53], v[112:113]
	v_pk_fma_f32 v[46:47], v[220:221], v[46:47], v[114:115]
	v_pk_fma_f32 v[48:49], v[222:223], v[48:49], v[116:117]
	v_pk_fma_f32 v[42:43], v[224:225], v[42:43], v[118:119]
	v_pk_fma_f32 v[44:45], v[226:227], v[44:45], v[120:121]
	v_pk_fma_f32 v[38:39], v[220:221], v[38:39], v[122:123]
	v_pk_fma_f32 v[40:41], v[222:223], v[40:41], v[124:125]
	v_pk_fma_f32 v[34:35], v[224:225], v[34:35], v[126:127]
	v_pk_fma_f32 v[36:37], v[226:227], v[36:37], v[128:129]
	global_store_dwordx4 v196, v[62:65], s[48:49]
	global_store_dwordx4 v196, v[58:61], s[48:49] offset:16
	global_store_dwordx4 v197, v[54:57], s[48:49]
	global_store_dwordx4 v197, v[50:53], s[48:49] offset:16
	global_store_dwordx4 v198, v[46:49], s[48:49]
	global_store_dwordx4 v198, v[42:45], s[48:49] offset:16
	global_store_dwordx4 v199, v[38:41], s[48:49]
	global_store_dwordx4 v199, v[34:37], s[48:49] offset:16
	s_waitcnt vmcnt(8)
	v_pk_fma_f32 v[146:147], v[146:147], v[212:213], v[212:213] op_sel:[0,1,0] op_sel_hi:[1,1,0]
	v_pk_fma_f32 v[148:149], v[148:149], v[212:213], v[212:213] op_sel:[0,1,0] op_sel_hi:[1,1,0]
	v_pk_fma_f32 v[150:151], v[150:151], v[212:213], v[212:213] op_sel:[0,1,0] op_sel_hi:[1,1,0]
	v_pk_fma_f32 v[152:153], v[152:153], v[212:213], v[212:213] op_sel:[0,1,0] op_sel_hi:[1,1,0]
	v_pk_fma_f32 v[154:155], v[154:155], v[214:215], v[214:215] op_sel:[0,1,0] op_sel_hi:[1,1,0]
	v_pk_fma_f32 v[156:157], v[156:157], v[214:215], v[214:215] op_sel:[0,1,0] op_sel_hi:[1,1,0]
	v_pk_fma_f32 v[158:159], v[158:159], v[214:215], v[214:215] op_sel:[0,1,0] op_sel_hi:[1,1,0]
	v_pk_fma_f32 v[160:161], v[160:161], v[214:215], v[214:215] op_sel:[0,1,0] op_sel_hi:[1,1,0]
	v_pk_fma_f32 v[162:163], v[162:163], v[216:217], v[216:217] op_sel:[0,1,0] op_sel_hi:[1,1,0]
	v_pk_fma_f32 v[164:165], v[164:165], v[216:217], v[216:217] op_sel:[0,1,0] op_sel_hi:[1,1,0]
	v_pk_fma_f32 v[166:167], v[166:167], v[216:217], v[216:217] op_sel:[0,1,0] op_sel_hi:[1,1,0]
	v_pk_fma_f32 v[168:169], v[168:169], v[216:217], v[216:217] op_sel:[0,1,0] op_sel_hi:[1,1,0]
	v_pk_fma_f32 v[170:171], v[170:171], v[218:219], v[218:219] op_sel:[0,1,0] op_sel_hi:[1,1,0]
	v_pk_fma_f32 v[172:173], v[172:173], v[218:219], v[218:219] op_sel:[0,1,0] op_sel_hi:[1,1,0]
	v_pk_fma_f32 v[174:175], v[174:175], v[218:219], v[218:219] op_sel:[0,1,0] op_sel_hi:[1,1,0]
	v_pk_fma_f32 v[176:177], v[176:177], v[218:219], v[218:219] op_sel:[0,1,0] op_sel_hi:[1,1,0]
	v_pk_add_f32 v[30:31], v[30:31], v[138:139]
	v_pk_add_f32 v[32:33], v[32:33], v[140:141]
	v_pk_add_f32 v[26:27], v[26:27], v[142:143]
	v_pk_add_f32 v[28:29], v[28:29], v[144:145]
	v_pk_add_f32 v[22:23], v[22:23], v[138:139]
	v_pk_add_f32 v[24:25], v[24:25], v[140:141]
	v_pk_add_f32 v[18:19], v[18:19], v[142:143]
	v_pk_add_f32 v[20:21], v[20:21], v[144:145]
	v_pk_add_f32 v[14:15], v[14:15], v[138:139]
	v_pk_add_f32 v[16:17], v[16:17], v[140:141]
	v_pk_add_f32 v[10:11], v[10:11], v[142:143]
	v_pk_add_f32 v[12:13], v[12:13], v[144:145]
	v_pk_add_f32 v[6:7], v[6:7], v[138:139]
	v_pk_add_f32 v[8:9], v[8:9], v[140:141]
	v_pk_add_f32 v[2:3], v[2:3], v[142:143]
	v_pk_add_f32 v[4:5], v[4:5], v[144:145]
	v_pk_fma_f32 v[30:31], v[228:229], v[30:31], v[146:147]
	v_pk_fma_f32 v[32:33], v[230:231], v[32:33], v[148:149]
	v_pk_fma_f32 v[26:27], v[232:233], v[26:27], v[150:151]
	v_pk_fma_f32 v[28:29], v[234:235], v[28:29], v[152:153]
	v_pk_fma_f32 v[22:23], v[228:229], v[22:23], v[154:155]
	v_pk_fma_f32 v[24:25], v[230:231], v[24:25], v[156:157]
	v_pk_fma_f32 v[18:19], v[232:233], v[18:19], v[158:159]
	v_pk_fma_f32 v[20:21], v[234:235], v[20:21], v[160:161]
	v_pk_fma_f32 v[14:15], v[228:229], v[14:15], v[162:163]
	v_pk_fma_f32 v[16:17], v[230:231], v[16:17], v[164:165]
	v_pk_fma_f32 v[10:11], v[232:233], v[10:11], v[166:167]
	v_pk_fma_f32 v[12:13], v[234:235], v[12:13], v[168:169]
	v_pk_fma_f32 v[6:7], v[228:229], v[6:7], v[170:171]
	v_pk_fma_f32 v[8:9], v[230:231], v[8:9], v[172:173]
	v_pk_fma_f32 v[2:3], v[232:233], v[2:3], v[174:175]
	v_pk_fma_f32 v[4:5], v[234:235], v[4:5], v[176:177]
	global_store_dwordx4 v196, v[30:33], s[48:49] offset:512
	global_store_dwordx4 v196, v[26:29], s[48:49] offset:528
	global_store_dwordx4 v197, v[22:25], s[48:49] offset:512
	global_store_dwordx4 v197, v[18:21], s[48:49] offset:528
	global_store_dwordx4 v198, v[14:17], s[48:49] offset:512
	global_store_dwordx4 v198, v[10:13], s[48:49] offset:528
	global_store_dwordx4 v199, v[6:9], s[48:49] offset:512
	global_store_dwordx4 v199, v[2:5], s[48:49] offset:528
	s_and_b64 vcc, exec, s[38:39]
	s_mov_b64 s[0:1], -1
	s_cbranch_vccnz .LBB0_300
	s_andn2_b64 vcc, exec, s[82:83]
	s_cbranch_vccnz .LBB0_299
	s_barrier
	s_branch .LBB0_299
